# P3 tail balancing: q-GEMM extra units and the CA sample units moved to workgroups that are otherwise lightly loaded
# baseline (speedup 1.0000x reference)
.LBB0_523:
	s_or_b64 exec, exec, s[40:41]
	v_readlane_b32 s0, v255, 22
	v_readlane_b32 s1, v255, 23
	s_xor_b64 s[78:79], s[0:1], -1
	v_mov_b32_e32 v10, v228
	s_waitcnt lgkmcnt(0)
	s_barrier
	s_mov_b32 s100, s62
	s_cmpk_lg_i32 s93, 0x100
	s_cbranch_scc1 .Lp3_noremap
	s_sub_i32 s100, 0xff, s62
.Lp3_noremap:
	s_cmpk_lt_i32 s100, 0x306
	s_nop 0
	v_readfirstlane_b32 s7, v10
	s_cbranch_scc0 .LBB0_569
	v_bfe_i32 v3, v10, 27, 1
	v_lshlrev_b32_e32 v2, 4, v10
	v_lshrrev_b32_e32 v3, 22, v3
	v_add_u32_e32 v3, v2, v3
	v_and_b32_e32 v3, 0xfffffc00, v3
	s_mul_hi_i32 s0, s100, 0x54abfd5b
	v_sub_u32_e32 v3, v2, v3
	s_lshr_b32 s1, s0, 31
	s_ashr_i32 s0, s0, 8
	v_ashrrev_i32_e32 v0, 31, v10
	v_lshrrev_b32_e32 v4, 4, v3
	s_add_i32 s0, s0, s1
	v_lshrrev_b32_e32 v0, 26, v0
	v_bitop3_b32 v4, v4, v3, 32 bitop3:0x6c
	v_ashrrev_i32_e32 v3, 31, v3
	s_mulk_i32 s0, 0x306
	v_add_u32_e32 v0, v10, v0
	v_lshrrev_b32_e32 v3, 26, v3
	s_sub_i32 s0, s100, s0
	v_ashrrev_i32_e32 v0, 6, v0
	v_add_u32_e32 v3, v4, v3
	s_sext_i32_i16 s1, s0
	v_lshlrev_b32_e32 v5, 3, v0
	v_ashrrev_i32_e32 v3, 6, v3
	s_mulk_i32 s1, 0x5556
	v_and_b32_e32 v5, -16, v5
	v_mul_i32_i24_e32 v6, 64, v3
	s_lshr_b32 s4, s1, 31
	s_lshr_b32 s1, s1, 16
	v_add_u32_e32 v5, v3, v5
	v_sub_u32_e32 v4, v4, v6
	v_mov_b32_e32 v8, 1
	s_add_i32 s6, s1, s4
	v_lshlrev_b32_e32 v0, 5, v0
	v_ashrrev_i16_sdwa v4, v8, sext(v4) dst_sel:DWORD dst_unused:UNUSED_PAD src0_sel:DWORD src1_sel:BYTE_0
	v_lshlrev_b32_e32 v6, 1, v5
	v_lshrrev_b32_e32 v7, 2, v5
	v_and_b32_e32 v3, 3, v3
	s_mov_b32 s8, 0x7fffe0
	s_mul_i32 s1, s6, 3
	v_and_b32_e32 v0, 32, v0
	v_bfe_i32 v4, v4, 0, 16
	v_and_b32_e32 v6, 24, v6
	v_and_b32_e32 v7, 4, v7
	v_and_or_b32 v3, v5, s8, v3
	s_sub_i32 s10, s0, s1
	v_or3_b32 v3, v3, v7, v6
	v_add_lshl_u32 v4, v0, v4, 1
	v_add_u32_e32 v2, 0x2000, v2
	s_add_u32 s28, s76, 0xaf92000
	v_lshl_add_u32 v138, v3, 9, v4
	v_ashrrev_i32_e32 v3, 31, v2
	s_addc_u32 s29, s77, 0
	s_bfe_i64 s[0:1], s[6:7], 0x100000
	v_lshrrev_b32_e32 v3, 22, v3
	s_lshl_b64 s[0:1], s[0:1], 17
	v_add_u32_e32 v3, v2, v3
	s_add_u32 s0, s28, s0
	v_ashrrev_i32_e32 v3, 10, v3
	s_addc_u32 s1, s29, s1
	v_readlane_b32 s4, v255, 44
	v_lshl_add_u32 v0, v5, 9, v4
	v_mul_i32_i24_e32 v4, 0x400, v3
	s_add_u32 s4, s76, s4
	v_sub_u32_e32 v2, v2, v4
	s_addc_u32 s5, s77, 0
	v_lshrrev_b32_e32 v4, 4, v2
	s_add_u32 s30, s4, 0xb00000
	v_bitop3_b32 v2, v4, v2, 32 bitop3:0x6c
	s_addc_u32 s31, s5, 0
	s_bfe_i64 s[4:5], s[10:11], 0x100000
	v_ashrrev_i32_e32 v5, 31, v2
	s_lshl_b64 s[4:5], s[4:5], 17
	v_lshrrev_b32_e32 v5, 26, v5
	s_add_u32 s4, s30, s4
	v_lshlrev_b32_e32 v4, 3, v3
	v_add_u32_e32 v5, v2, v5
	s_addc_u32 s5, s31, s5
	v_and_b32_e32 v4, -16, v4
	v_ashrrev_i32_e32 v6, 6, v5
	v_and_b32_e32 v5, 0xc0, v5
	s_ashr_i32 s15, s7, 6
	v_add_u32_e32 v4, v6, v4
	v_sub_u32_e32 v2, v2, v5
	s_lshl_b32 s34, s15, 10
	v_lshlrev_b32_e32 v3, 5, v3
	v_ashrrev_i16_sdwa v2, v8, sext(v2) dst_sel:DWORD dst_unused:UNUSED_PAD src0_sel:DWORD src1_sel:BYTE_0
	v_lshlrev_b32_e32 v5, 1, v4
	v_lshrrev_b32_e32 v7, 2, v4
	v_and_b32_e32 v6, 3, v6
	s_add_i32 s35, s34, 0
	v_and_b32_e32 v3, 32, v3
	v_bfe_i32 v2, v2, 0, 16
	v_and_b32_e32 v5, 24, v5
	v_and_b32_e32 v7, 4, v7
	v_and_or_b32 v6, v4, s8, v6
	s_add_i32 m0, s35, 0x10000
	s_ashr_i32 s14, s7, 8
	v_or3_b32 v5, v6, v7, v5
	v_add_lshl_u32 v2, v3, v2, 1
	global_load_lds_dwordx4 v138, s[4:5]
	s_add_i32 m0, s35, 0x12000
	v_lshl_add_u32 v142, v5, 9, v2
	s_add_u32 s8, s4, 0x10000
	global_load_lds_dwordx4 v142, s[4:5]
	s_addc_u32 s9, s5, 0
	s_add_i32 m0, s35, 0x14000
	s_add_i32 s36, s35, 0x2000
	global_load_lds_dwordx4 v138, s[8:9]
	s_add_i32 m0, s35, 0x16000
	v_lshl_add_u32 v140, v4, 9, v2
	global_load_lds_dwordx4 v142, s[8:9]
	s_mov_b32 m0, s35
	s_add_u32 s8, s0, 0x10000
	global_load_lds_dwordx4 v0, s[0:1]
	s_mov_b32 m0, s36
	s_addc_u32 s9, s1, 0
	s_add_i32 s37, s35, 0x4000
	global_load_lds_dwordx4 v140, s[0:1]
	s_mov_b32 m0, s37
	s_add_i32 s40, s35, 0x6000
	global_load_lds_dwordx4 v0, s[8:9]
	s_mov_b32 m0, s40
	v_mov_b32_e32 v139, v1
	global_load_lds_dwordx4 v140, s[8:9]
	v_mov_b32_e32 v143, v1
	v_mov_b32_e32 v141, v1
	s_cmp_eq_u32 s14, 1
	v_lshl_add_u64 v[8:9], s[4:5], 0, v[138:139]
	v_lshl_add_u64 v[6:7], s[4:5], 0, v[142:143]
	v_lshl_add_u64 v[2:3], s[0:1], 0, v[0:1]
	s_cselect_b64 s[8:9], -1, 0
	s_cmp_lg_u32 s14, 1
	v_lshl_add_u64 v[4:5], s[0:1], 0, v[140:141]
	s_cbranch_scc1 .LBB0_526
	s_barrier
.LBB0_526:
	s_sext_i32_i16 s46, s10
	v_readlane_b32 s10, v255, 49
	v_readlane_b32 s11, v255, 50
	s_lshl_b32 s68, s10, 5
	v_readlane_b32 s16, v255, 36
	s_lshl_b64 s[10:11], s[68:69], 2
	v_readlane_b32 s18, v255, 38
	v_readlane_b32 s12, v255, 47
	v_readlane_b32 s19, v255, 39
	s_add_u32 s10, s18, s10
	v_readlane_b32 s13, v255, 48
	s_addc_u32 s11, s19, s11
	s_lshl_b64 s[12:13], s[12:13], 2
	v_and_b32_e32 v11, 15, v10
	v_readlane_b32 s17, v255, 37
	s_add_u32 s12, s16, s12
	v_and_b32_e32 v12, 48, v10
	v_lshlrev_b32_e32 v11, 6, v11
	v_lshlrev_b32_e32 v10, 2, v10
	s_addc_u32 s13, s17, s13
	v_or_b32_e32 v13, v11, v12
	s_lshl_b32 s14, s14, 13
	v_and_b32_e32 v10, 32, v10
	v_bitop3_b32 v11, v11, v10, v12 bitop3:0x36
	v_bitop3_b32 v10, v13, s14, v10 bitop3:0xde
	s_lshl_b32 s14, s15, 12
	s_add_i32 m0, s35, 0x18000
	v_lshl_add_u64 v[8:9], v[8:9], 0, s[70:71]
	s_and_b32 s14, s14, 0x3000
	s_waitcnt vmcnt(2)
	s_barrier
	global_load_lds_dwordx4 v[8:9], off
	v_lshl_add_u64 v[6:7], v[6:7], 0, s[70:71]
	s_add_i32 m0, s35, 0x1a000
	s_add_i32 s41, s35, 0x8000
	s_add_i32 s42, s35, 0xa000
	v_or_b32_e32 v147, s14, v11
	global_load_lds_dwordx4 v[6:7], off
	v_lshl_add_u64 v[2:3], v[2:3], 0, s[70:71]
	s_mov_b32 m0, s41
	s_add_u32 s14, s4, 0x10080
	global_load_lds_dwordx4 v[2:3], off
	v_lshl_add_u64 v[2:3], v[4:5], 0, s[70:71]
	s_mov_b32 m0, s42
	s_addc_u32 s15, s5, 0
	global_load_lds_dwordx4 v[2:3], off
	s_add_i32 m0, s35, 0x1c000
	v_lshl_add_u64 v[2:3], s[14:15], 0, v[138:139]
	global_load_lds_dwordx4 v[2:3], off
	v_lshl_add_u64 v[2:3], s[14:15], 0, v[142:143]
	s_add_i32 m0, s35, 0x1e000
	s_cmpk_lt_u32 s7, 0x100
	global_load_lds_dwordx4 v[2:3], off
	s_waitcnt vmcnt(6)
	s_sext_i32_i16 s6, s6
	s_cselect_b64 s[14:15], -1, 0
	s_add_i32 s43, s93, s100
	v_add_u32_e32 v182, 0, v10
	s_mov_b64 s[18:19], s[4:5]
	s_mov_b64 s[16:17], s[0:1]
	v_readlane_b32 s20, v255, 40
	v_readlane_b32 s21, v255, 41
	v_readlane_b32 s22, v255, 42
	v_readlane_b32 s23, v255, 43
	s_barrier
	s_branch .LBB0_529

.LBB0_737:
	s_add_i32 s42, s42, 1
	s_mul_i32 s6, s42, s93
	s_add_i32 s6, s6, s62
	s_cmpk_lg_i32 s93, 0x100
	s_cbranch_scc1 .Lca_noremap
	s_cmpk_lt_i32 s6, 0x400
	s_cbranch_scc1 .Lca_noremap
	s_sub_i32 s6, s6, 0xe0
	s_cmpk_lt_i32 s6, 0x400
	s_cbranch_scc1 .LBB0_799
.Lca_noremap:
	s_cmpk_lt_i32 s6, 0x420
	s_cbranch_scc0 .LBB0_799
